# lru_pass: next-item XS rows prefetched by LDS-DMA into a stage + gv DMA before scan + constants cache (compact) + conv weights cache
# speedup vs baseline: 1.0283x; 1.0080x over previous
; #define LAS __attribute__((address_space(3)))
; __device__ __forceinline__ int otid() { int t = __builtin_amdgcn_workitem_id_x(); asm volatile("" : "+v"(t)); return t; }
; __device__ __forceinline__ int obid() { int b = __builtin_amdgcn_workgroup_id_x(); asm volatile("" : "+s"(b)); return b; }
; __device__ __forceinline__ void lru_pass(LAS unsigned char* L, int mode, const bf16_t* Z, const bf16_t* LWT, const float* conv_w, const float* conv_b, const float* b_a, const float* b_x, const float* lam,
;                          float* LSUM, const float* LCAR, bf16_t* Y) {
;     LAS float* xc = (LAS float*)L; LAS bf16_t* xcb = (LAS bf16_t*)(xc + 64 * 65); LAS bf16_t* LW = xcb + 64 * 72; LAS float* AA = (LAS float*)(LW + 4 * 64 * 72); LAS float* UU = AA + 2 * 64 * 65;
;     const int tid = otid(), wid = tid >> 6, lane = tid & 63, fr = lane & 15, fq = lane >> 4;
;     int nprev = -1;
;     for (int item = obid(); item < 4096; item += gridDim.x) {
;         const int b = item >> 11, seg = (item >> 3) & 255, n = item & 7;
;     ...
;         if (tid < 128) { const int g = tid >> 6, d = tid & 63, ch = n * 64 + d; const size_t ix = ((size_t)(b * 256 + seg) * 2 + g) * 512 + ch;
;             if (mode == 0) { float P = 1.f, E = 0.f;
;                 for (int st = 0; st < 64; ++st) { const int i = g ? 63 - st : st; const float a_ = AA[g * 4160 + i * 65 + d]; E = a_ * E + UU[g * 4160 + i * 65 + d]; P *= a_; }
;                 LSUM[2 * ix] = P; LSUM[2 * ix + 1] = E; }
;             else { float hc = LCAR[ix];
;                 for (int st = 0; st < 64; ++st) { const int i = g ? 63 - st : st; hc = AA[g * 4160 + i * 65 + d] * hc + UU[g * 4160 + i * 65 + d]; UU[g * 4160 + i * 65 + d] = hc; } } }
.LBB0_587:
	s_andn2_b64 vcc, exec, s[20:21]
	s_cbranch_vccnz .LBB0_625
	v_mov_b32_e32 v1, v196
	s_mov_b32 s38, s82
	s_cmpk_gt_i32 s38, 0xfff
	s_cbranch_scc1 .LBB0_625
	s_lshl_b32 s4, s95, 11
	s_ashr_i32 s5, s4, 31
	v_readlane_b32 s40, v254, 1
	s_lshl_b64 s[4:5], s[4:5], 2
	v_readlane_b32 s46, v254, 7
	v_readlane_b32 s48, v254, 9
	v_readlane_b32 s47, v254, 8
	v_readlane_b32 s49, v254, 10
	s_add_u32 s46, s48, s4
	s_addc_u32 s47, s49, s5
	s_lshl_b32 s4, s95, 9
	s_ashr_i32 s5, s4, 31
	v_readlane_b32 s50, v254, 11
	s_lshl_b64 s[4:5], s[4:5], 2
	v_readlane_b32 s51, v254, 12
	s_add_u32 s48, s50, s4
	s_addc_u32 s49, s51, s5
	s_lshl_b32 s4, s95, 10
	s_ashr_i32 s5, s4, 31
	v_readlane_b32 s54, v254, 15
	s_lshl_b64 s[4:5], s[4:5], 2
	v_readlane_b32 s55, v254, 16
	s_add_u32 s50, s54, s4
	v_readlane_b32 s20, v253, 20
	v_readlane_b32 s52, v254, 13
	s_addc_u32 s51, s55, s5
	v_readlane_b32 s22, v253, 22
	v_readlane_b32 s53, v254, 14
	v_readlane_b32 s23, v253, 23
	s_add_u32 s52, s22, s4
	v_readlane_b32 s24, v253, 24
	s_addc_u32 s53, s23, s5
	v_readlane_b32 s41, v254, 2
	s_add_u32 s54, s24, s4
	s_movk_i32 s4, 0x217
	v_readlane_b32 s42, v254, 3
	v_readlane_b32 s43, v254, 4
	v_cmp_lt_i32_e64 s[40:41], s4, v1
	s_movk_i32 s4, 0x80
	s_waitcnt vmcnt(0)
	v_ashrrev_i32_e32 v6, 6, v1
	v_ashrrev_i32_e32 v2, 8, v1
	s_movk_i32 s2, 0x2400
	v_cmp_gt_i32_e64 s[42:43], s4, v1
	s_movk_i32 s4, 0x1040
	v_lshlrev_b32_e32 v4, 4, v6
	v_mad_i32_i24 v8, v2, s2, 0
	v_lshlrev_b32_e32 v55, 9, v2
	v_mul_i32_i24_e32 v10, 0x1040, v2
	v_mul_lo_u32 v2, v6, s4
	s_movk_i32 s4, 0x48
	v_and_b32_e32 v41, 63, v1
	v_and_b32_e32 v34, 15, v1
	v_and_b32_e32 v4, 48, v4
	v_mul_lo_u32 v12, v6, s4
	v_or_b32_e32 v5, v4, v34
	v_readlane_b32 s3, v253, 7
	v_add_lshl_u32 v12, v12, v41, 1
	v_mul_lo_u32 v13, v6, s13
	v_lshlrev_b32_e32 v14, 1, v41
	v_mul_u32_u24_e32 v5, 0x90, v5
	v_lshrrev_b32_e32 v7, 2, v1
	v_add_u32_e32 v57, s3, v12
	v_add3_u32 v58, s3, v13, v14
	v_add_u32_e32 v59, 0, v12
	v_mul_u32_u24_e32 v12, 0x48, v34
	v_and_b32_e32 v13, 48, v1
	v_and_or_b32 v9, v7, 12, v4
	v_lshlrev_b32_e32 v4, 4, v1
	v_add3_u32 v66, 0, v5, v13
	v_lshlrev_b32_e32 v5, 1, v12
	v_and_b32_e32 v4, 0x70, v4
	v_add3_u32 v67, v8, v13, v5
	v_or_b32_e32 v5, v10, v34
	v_mul_u32_u24_e32 v10, 0x41, v9
	v_ashrrev_i32_e32 v7, 31, v6
	v_ashrrev_i32_e32 v92, 3, v1
	s_movk_i32 s2, 0x104
	v_add_u32_e32 v40, s3, v4
	v_lshlrev_b32_e32 v8, 2, v34
	v_lshlrev_b32_e32 v13, 2, v10
	s_movk_i32 s3, 0x41
	v_lshlrev_b64 v[198:199], 9, v[6:7]
	v_mul_lo_u32 v11, v92, s2
	v_mul_lo_u32 v6, v6, s2
	v_add_lshl_u32 v12, v10, v5, 2
	v_add3_u32 v69, 0, v8, v13
	v_readlane_b32 s2, v253, 6
	v_mad_u32_u24 v8, v9, s3, s3
	v_add_u32_e32 v68, 0, v12
	v_add_u32_e32 v70, s2, v12
	v_add_u32_e32 v12, v8, v5
	v_mov_b32_e32 v16, 0x82
	v_lshl_add_u32 v71, v12, 2, s2
	v_mad_u32_u24 v12, v9, s3, v16
	v_mov_b32_e32 v17, 0xc3
	v_add_u32_e32 v13, v12, v5
	v_mad_u32_u24 v9, v9, s3, v17
	v_lshl_add_u32 v72, v13, 2, s2
	v_add_u32_e32 v13, v9, v5
	v_lshl_add_u32 v73, v13, 2, s2
	v_or_b32_e32 v13, 16, v5
	v_add_lshl_u32 v14, v10, v13, 2
	v_add_u32_e32 v74, s2, v14
	v_add_u32_e32 v15, v8, v13
	v_add_u32_e32 v75, 0, v14
	v_add_u32_e32 v14, v12, v13
	v_add_u32_e32 v13, v9, v13
	v_lshl_add_u32 v78, v13, 2, s2
	v_or_b32_e32 v13, 32, v5
	v_or_b32_e32 v5, 48, v5
	v_lshl_add_u32 v76, v15, 2, s2
	v_add_u32_e32 v15, v8, v13
	v_add_u32_e32 v8, v8, v5
	v_readlane_b32 s44, v254, 5
	v_readlane_b32 s45, v254, 6
	v_lshl_add_u32 v86, v8, 2, s2
	v_add_u32_e32 v8, v12, v5
	v_lshl_add_u32 v77, v14, 2, s2
	v_add_lshl_u32 v14, v10, v13, 2
	v_add_lshl_u32 v10, v10, v5, 2
	v_lshl_add_u32 v87, v8, 2, s2
	v_add_u32_e32 v5, v9, v5
	v_cmp_gt_u32_e64 s[44:45], 64, v1
	v_mov_b32_e32 v8, 0xfff
	v_or_b32_e32 v7, v2, v41
	v_lshl_add_u32 v88, v5, 2, s2
	v_cndmask_b32_e64 v5, v8, 0, s[44:45]
	v_add_u32_e32 v79, s2, v14
	v_add_u32_e32 v80, 0, v14
	v_add_u32_e32 v14, v12, v13
	v_add_u32_e32 v13, v9, v13
	v_add_u32_e32 v84, s2, v10
	v_add_u32_e32 v85, 0, v10
	v_add_lshl_u32 v5, v7, v5, 2
	v_mov_b32_e32 v9, 0xfbe
	v_mov_b32_e32 v10, 0x41
	v_add_u32_e32 v95, 0, v5
	v_add_u32_e32 v56, s2, v5
	v_cndmask_b32_e64 v5, v9, v10, s[44:45]
	v_add_lshl_u32 v5, v7, v5, 2
	v_mov_b32_e32 v12, 0xf7d
	v_add_u32_e32 v202, 0, v5
	v_add_u32_e32 v201, s2, v5
	v_cndmask_b32_e64 v5, v12, v16, s[44:45]
	v_lshl_add_u32 v83, v13, 2, s2
	v_add_lshl_u32 v5, v7, v5, 2
	v_mov_b32_e32 v13, 0xf3c
	v_add_u32_e32 v96, 0, v5
	v_add_u32_e32 v89, s2, v5
	v_cndmask_b32_e64 v5, v13, v17, s[44:45]
	v_lshl_add_u32 v81, v15, 2, s2
	v_lshl_add_u32 v82, v14, 2, s2
	v_add_lshl_u32 v5, v7, v5, 2
	v_mov_b32_e32 v14, 0xefb
	v_mov_b32_e32 v15, 0x104
	v_add_u32_e32 v249, 0, v5
	v_add_u32_e32 v250, s2, v5
	v_cndmask_b32_e64 v5, v14, v15, s[44:45]
	v_add_lshl_u32 v5, v7, v5, 2
	s_waitcnt lgkmcnt(0)
; __device__ __forceinline__ void lru_pass(LAS unsigned char* L, int mode, const bf16_t* Z, const bf16_t* LWT, const float* conv_w, const float* conv_b, const float* b_a, const float* b_x, const float* lam,
;                          float* LSUM, const float* LCAR, bf16_t* Y) {
;     ...
;         if (tid < 128) { const int g = tid >> 6, d = tid & 63, ch = n * 64 + d; const size_t ix = ((size_t)(b * 256 + seg) * 2 + g) * 512 + ch;
;             if (mode == 0) { float P = 1.f, E = 0.f;
;                 for (int st = 0; st < 64; ++st) { const int i = g ? 63 - st : st; const float a_ = AA[g * 4160 + i * 65 + d]; E = a_ * E + UU[g * 4160 + i * 65 + d]; P *= a_; }
;                 LSUM[2 * ix] = P; LSUM[2 * ix + 1] = E; }
;             else { float hc = LCAR[ix];
;                 for (int st = 0; st < 64; ++st) { const int i = g ? 63 - st : st; hc = AA[g * 4160 + i * 65 + d] * hc + UU[g * 4160 + i * 65 + d]; UU[g * 4160 + i * 65 + d] = hc; } } }
	v_mov_b32_e32 v18, 0xeba
	v_mov_b32_e32 v19, 0x145
	v_add_u32_e32 v203, 0, v5
	v_add_u32_e32 v98, s2, v5
	v_cndmask_b32_e64 v5, v18, v19, s[44:45]
	v_add_lshl_u32 v5, v7, v5, 2
	v_mov_b32_e32 v20, 0xe79
	v_mov_b32_e32 v21, 0x186
	v_add_u32_e32 v99, 0, v5
	v_add_u32_e32 v100, s2, v5
	v_cndmask_b32_e64 v5, v20, v21, s[44:45]
	v_add_lshl_u32 v5, v7, v5, 2
	v_mov_b32_e32 v22, 0xe38
	v_mov_b32_e32 v23, 0x1c7
	v_add_u32_e32 v101, 0, v5
	v_add_u32_e32 v102, s2, v5
	v_cndmask_b32_e64 v5, v22, v23, s[44:45]
	v_add_lshl_u32 v5, v7, v5, 2
	v_mov_b32_e32 v24, 0xdf7
	v_mov_b32_e32 v25, 0x208
	v_add_u32_e32 v103, 0, v5
	v_add_u32_e32 v104, s2, v5
	v_cndmask_b32_e64 v5, v24, v25, s[44:45]
	v_add_lshl_u32 v5, v7, v5, 2
	v_mov_b32_e32 v26, 0xdb6
	v_mov_b32_e32 v27, 0x249
	v_add_u32_e32 v105, 0, v5
	v_add_u32_e32 v106, s2, v5
	v_cndmask_b32_e64 v5, v26, v27, s[44:45]
	v_add_lshl_u32 v5, v7, v5, 2
	v_mov_b32_e32 v28, 0xd75
	v_mov_b32_e32 v29, 0x28a
	v_add_u32_e32 v107, 0, v5
	v_add_u32_e32 v108, s2, v5
	v_cndmask_b32_e64 v5, v28, v29, s[44:45]
	v_add_lshl_u32 v5, v7, v5, 2
	v_mov_b32_e32 v30, 0xd34
	v_mov_b32_e32 v31, 0x2cb
	v_add_u32_e32 v109, 0, v5
	v_add_u32_e32 v110, s2, v5
	v_cndmask_b32_e64 v5, v30, v31, s[44:45]
	v_add_lshl_u32 v5, v7, v5, 2
	v_mov_b32_e32 v32, 0xcf3
	v_mov_b32_e32 v33, 0x30c
	v_add_u32_e32 v111, 0, v5
	v_add_u32_e32 v112, s2, v5
	v_cndmask_b32_e64 v5, v32, v33, s[44:45]
	v_add_lshl_u32 v5, v7, v5, 2
	v_mov_b32_e32 v35, 0xcb2
	v_mov_b32_e32 v36, 0x34d
	v_add_u32_e32 v113, 0, v5
	v_add_u32_e32 v114, s2, v5
	v_cndmask_b32_e64 v5, v35, v36, s[44:45]
	v_add_lshl_u32 v5, v7, v5, 2
	v_mov_b32_e32 v37, 0xc71
	v_mov_b32_e32 v38, 0x38e
	v_add_u32_e32 v115, 0, v5
	v_add_u32_e32 v116, s2, v5
	v_cndmask_b32_e64 v5, v37, v38, s[44:45]
	v_add_lshl_u32 v5, v7, v5, 2
	v_mov_b32_e32 v39, 0xc30
	v_mov_b32_e32 v42, 0x3cf
	v_add_u32_e32 v117, 0, v5
	v_add_u32_e32 v118, s2, v5
	v_cndmask_b32_e64 v5, v39, v42, s[44:45]
	v_add_lshl_u32 v5, v7, v5, 2
	v_mov_b32_e32 v43, 0xbef
	v_mov_b32_e32 v44, 0x410
	v_add_u32_e32 v119, 0, v5
	v_add_u32_e32 v120, s2, v5
	v_cndmask_b32_e64 v5, v43, v44, s[44:45]
	v_add_lshl_u32 v5, v7, v5, 2
	v_mov_b32_e32 v45, 0xbae
	v_mov_b32_e32 v46, 0x451
	v_add_u32_e32 v121, 0, v5
	v_add_u32_e32 v122, s2, v5
	v_cndmask_b32_e64 v5, v45, v46, s[44:45]
	v_add_lshl_u32 v5, v7, v5, 2
	v_mov_b32_e32 v47, 0xb6d
	v_mov_b32_e32 v48, 0x492
	v_add_u32_e32 v123, 0, v5
	v_add_u32_e32 v124, s2, v5
	v_cndmask_b32_e64 v5, v47, v48, s[44:45]
	v_add_lshl_u32 v5, v7, v5, 2
	v_mov_b32_e32 v49, 0xb2c
	v_mov_b32_e32 v50, 0x4d3
	v_add_u32_e32 v125, 0, v5
	v_add_u32_e32 v126, s2, v5
	v_cndmask_b32_e64 v5, v49, v50, s[44:45]
	v_add_lshl_u32 v5, v7, v5, 2
	v_mov_b32_e32 v51, 0xaeb
	v_mov_b32_e32 v52, 0x514
	v_add_u32_e32 v127, 0, v5
	v_add_u32_e32 v128, s2, v5
	v_cndmask_b32_e64 v5, v51, v52, s[44:45]
	v_add_lshl_u32 v5, v7, v5, 2
	v_mov_b32_e32 v53, 0xaaa
	v_mov_b32_e32 v54, 0x555
	v_add_u32_e32 v129, 0, v5
	v_add_u32_e32 v130, s2, v5
	v_cndmask_b32_e64 v5, v53, v54, s[44:45]
	v_add_lshl_u32 v5, v7, v5, 2
	v_mov_b32_e32 v90, 0xa69
	v_mov_b32_e32 v91, 0x596
	v_add_u32_e32 v131, 0, v5
	v_add_u32_e32 v132, s2, v5
	v_cndmask_b32_e64 v5, v90, v91, s[44:45]
	v_add_lshl_u32 v5, v7, v5, 2
	v_mov_b32_e32 v155, 0xa28
	v_mov_b32_e32 v171, 0x5d7
	v_add_u32_e32 v133, 0, v5
	v_add_u32_e32 v134, s2, v5
	v_cndmask_b32_e64 v5, v155, v171, s[44:45]
	v_add_lshl_u32 v5, v7, v5, 2
	v_mov_b32_e32 v169, 0x9e7
	v_mov_b32_e32 v170, 0x618
	v_add_u32_e32 v135, 0, v5
	v_add_u32_e32 v136, s2, v5
	v_cndmask_b32_e64 v5, v169, v170, s[44:45]
	v_add_lshl_u32 v5, v7, v5, 2
	v_mov_b32_e32 v167, 0x9a6
	v_mov_b32_e32 v168, 0x659
	v_add_u32_e32 v137, 0, v5
	v_add_u32_e32 v138, s2, v5
	v_cndmask_b32_e64 v5, v167, v168, s[44:45]
	v_add_lshl_u32 v5, v7, v5, 2
	v_mov_b32_e32 v165, 0x965
	v_mov_b32_e32 v166, 0x69a
	v_add_u32_e32 v139, 0, v5
	v_add_u32_e32 v140, s2, v5
	v_cndmask_b32_e64 v5, v165, v166, s[44:45]
	v_add_lshl_u32 v5, v7, v5, 2
	v_mov_b32_e32 v163, 0x924
	v_mov_b32_e32 v164, 0x6db
	v_add_u32_e32 v141, 0, v5
	v_add_u32_e32 v142, s2, v5
	v_cndmask_b32_e64 v5, v163, v164, s[44:45]
	v_add_lshl_u32 v5, v7, v5, 2
	v_mov_b32_e32 v161, 0x8e3
	v_mov_b32_e32 v162, 0x71c
	v_add_u32_e32 v143, 0, v5
	v_add_u32_e32 v144, s2, v5
	v_cndmask_b32_e64 v5, v161, v162, s[44:45]
	v_add_lshl_u32 v5, v7, v5, 2
	v_mov_b32_e32 v159, 0x8a2
	v_mov_b32_e32 v160, 0x75d
	v_add_u32_e32 v145, 0, v5
	v_add_u32_e32 v146, s2, v5
	v_cndmask_b32_e64 v5, v159, v160, s[44:45]
	v_add_lshl_u32 v5, v7, v5, 2
	v_mov_b32_e32 v157, 0x861
	v_mov_b32_e32 v158, 0x79e
	v_add_u32_e32 v147, 0, v5
	v_add_u32_e32 v148, s2, v5
	v_cndmask_b32_e64 v5, v157, v158, s[44:45]
	v_add_lshl_u32 v5, v7, v5, 2
	v_mov_b32_e32 v153, 0x820
	v_mov_b32_e32 v156, 0x7df
	v_add_u32_e32 v149, 0, v5
	v_add_u32_e32 v150, s2, v5
	v_cndmask_b32_e64 v5, v153, v156, s[44:45]
	v_add_lshl_u32 v5, v7, v5, 2
	v_add_u32_e32 v151, 0, v5
	v_add_u32_e32 v152, s2, v5
	v_cndmask_b32_e64 v5, v156, v153, s[44:45]
	v_add_lshl_u32 v5, v7, v5, 2
	v_add_u32_e32 v153, 0, v5
; #define LAS __attribute__((address_space(3)))
; __device__ __forceinline__ int otid() { int t = __builtin_amdgcn_workitem_id_x(); asm volatile("" : "+v"(t)); return t; }
; __device__ __forceinline__ int obid() { int b = __builtin_amdgcn_workgroup_id_x(); asm volatile("" : "+s"(b)); return b; }
; __device__ __forceinline__ void lru_pass(LAS unsigned char* L, int mode, const bf16_t* Z, const bf16_t* LWT, const float* conv_w, const float* conv_b, const float* b_a, const float* b_x, const float* lam,
;                          float* LSUM, const float* LCAR, bf16_t* Y) {
;     LAS float* xc = (LAS float*)L; LAS bf16_t* xcb = (LAS bf16_t*)(xc + 64 * 65); LAS bf16_t* LW = xcb + 64 * 72; LAS float* AA = (LAS float*)(LW + 4 * 64 * 72); LAS float* UU = AA + 2 * 64 * 65;
;     const int tid = otid(), wid = tid >> 6, lane = tid & 63, fr = lane & 15, fq = lane >> 4;
;     int nprev = -1;
;     for (int item = obid(); item < 4096; item += gridDim.x) {
;         const int b = item >> 11, seg = (item >> 3) & 255, n = item & 7;
;     ...
;         if (tid < 128) { const int g = tid >> 6, d = tid & 63, ch = n * 64 + d; const size_t ix = ((size_t)(b * 256 + seg) * 2 + g) * 512 + ch;
;             if (mode == 0) { float P = 1.f, E = 0.f;
;                 for (int st = 0; st < 64; ++st) { const int i = g ? 63 - st : st; const float a_ = AA[g * 4160 + i * 65 + d]; E = a_ * E + UU[g * 4160 + i * 65 + d]; P *= a_; }
;                 LSUM[2 * ix] = P; LSUM[2 * ix + 1] = E; }
;             else { float hc = LCAR[ix];
;                 for (int st = 0; st < 64; ++st) { const int i = g ? 63 - st : st; hc = AA[g * 4160 + i * 65 + d] * hc + UU[g * 4160 + i * 65 + d]; UU[g * 4160 + i * 65 + d] = hc; } } }
;         __syncthreads();
;         if (mode == 1) {
	v_add_u32_e32 v156, s2, v5
	v_cndmask_b32_e64 v5, v158, v157, s[44:45]
	v_add_lshl_u32 v5, v7, v5, 2
	v_add_u32_e32 v157, 0, v5
	v_add_u32_e32 v158, s2, v5
	v_cndmask_b32_e64 v5, v160, v159, s[44:45]
	v_add_lshl_u32 v5, v7, v5, 2
	v_add_u32_e32 v159, 0, v5
	v_add_u32_e32 v160, s2, v5
	v_cndmask_b32_e64 v5, v162, v161, s[44:45]
	v_add_lshl_u32 v5, v7, v5, 2
	v_add_u32_e32 v161, 0, v5
	v_add_u32_e32 v162, s2, v5
	v_cndmask_b32_e64 v5, v164, v163, s[44:45]
	v_add_lshl_u32 v5, v7, v5, 2
	v_add_u32_e32 v163, 0, v5
	v_add_u32_e32 v164, s2, v5
	v_cndmask_b32_e64 v5, v166, v165, s[44:45]
	v_add_lshl_u32 v5, v7, v5, 2
	v_add_u32_e32 v165, 0, v5
	v_add_u32_e32 v166, s2, v5
	v_cndmask_b32_e64 v5, v168, v167, s[44:45]
	v_add_lshl_u32 v5, v7, v5, 2
	v_add_u32_e32 v167, 0, v5
	v_add_u32_e32 v168, s2, v5
	v_cndmask_b32_e64 v5, v170, v169, s[44:45]
	v_add_lshl_u32 v5, v7, v5, 2
	v_add_u32_e32 v169, 0, v5
	v_add_u32_e32 v170, s2, v5
	v_cndmask_b32_e64 v5, v171, v155, s[44:45]
	v_add_lshl_u32 v5, v7, v5, 2
	v_add_u32_e32 v171, 0, v5
	v_add_u32_e32 v172, s2, v5
	v_cndmask_b32_e64 v5, v91, v90, s[44:45]
	v_add_lshl_u32 v5, v7, v5, 2
	v_add_u32_e32 v173, 0, v5
	v_add_u32_e32 v174, s2, v5
	v_cndmask_b32_e64 v5, v54, v53, s[44:45]
	v_add_lshl_u32 v5, v7, v5, 2
	v_add_u32_e32 v175, 0, v5
	v_add_u32_e32 v176, s2, v5
	v_cndmask_b32_e64 v5, v52, v51, s[44:45]
	v_add_lshl_u32 v5, v7, v5, 2
	v_add_u32_e32 v177, 0, v5
	v_add_u32_e32 v178, s2, v5
	v_cndmask_b32_e64 v5, v50, v49, s[44:45]
	v_add_lshl_u32 v5, v7, v5, 2
	v_add_u32_e32 v179, 0, v5
	v_add_u32_e32 v180, s2, v5
	v_cndmask_b32_e64 v5, v48, v47, s[44:45]
	v_add_lshl_u32 v5, v7, v5, 2
	v_add_u32_e32 v181, 0, v5
	v_add_u32_e32 v182, s2, v5
	v_cndmask_b32_e64 v5, v46, v45, s[44:45]
	v_add_lshl_u32 v5, v7, v5, 2
	v_add_u32_e32 v183, 0, v5
	v_add_u32_e32 v184, s2, v5
	v_cndmask_b32_e64 v5, v44, v43, s[44:45]
	v_add_lshl_u32 v5, v7, v5, 2
	v_add_u32_e32 v185, 0, v5
	v_add_u32_e32 v186, s2, v5
	v_cndmask_b32_e64 v5, v42, v39, s[44:45]
	v_add_lshl_u32 v5, v7, v5, 2
	v_add_u32_e32 v187, 0, v5
	v_add_u32_e32 v188, s2, v5
	v_cndmask_b32_e64 v5, v38, v37, s[44:45]
	v_add_lshl_u32 v5, v7, v5, 2
	v_add_u32_e32 v189, 0, v5
	v_add_u32_e32 v190, s2, v5
	v_cndmask_b32_e64 v5, v36, v35, s[44:45]
	v_add_lshl_u32 v5, v7, v5, 2
	v_add_u32_e32 v191, 0, v5
	v_add_u32_e32 v192, s2, v5
	v_cndmask_b32_e64 v5, v33, v32, s[44:45]
	v_add_lshl_u32 v5, v7, v5, 2
	v_add_u32_e32 v193, 0, v5
	v_add_u32_e32 v194, s2, v5
	v_cndmask_b32_e64 v5, v31, v30, s[44:45]
	v_add_lshl_u32 v5, v7, v5, 2
	v_add_u32_e32 v195, 0, v5
	v_add_u32_e32 v223, s2, v5
	v_cndmask_b32_e64 v5, v29, v28, s[44:45]
	v_add_lshl_u32 v5, v7, v5, 2
	v_add_u32_e32 v224, 0, v5
	v_add_u32_e32 v225, s2, v5
	v_cndmask_b32_e64 v5, v27, v26, s[44:45]
	v_add_lshl_u32 v5, v7, v5, 2
	v_add_u32_e32 v226, 0, v5
	v_add_u32_e32 v227, s2, v5
	v_cndmask_b32_e64 v5, v25, v24, s[44:45]
	v_add_lshl_u32 v5, v7, v5, 2
	v_add_u32_e32 v228, 0, v5
	v_add_u32_e32 v229, s2, v5
	v_cndmask_b32_e64 v5, v23, v22, s[44:45]
	v_add_lshl_u32 v5, v7, v5, 2
	v_add_u32_e32 v230, 0, v5
	v_add_u32_e32 v231, s2, v5
	v_cndmask_b32_e64 v5, v21, v20, s[44:45]
	v_add_lshl_u32 v5, v7, v5, 2
	v_add_u32_e32 v232, 0, v5
	v_add_u32_e32 v233, s2, v5
	v_cndmask_b32_e64 v5, v19, v18, s[44:45]
	v_add_lshl_u32 v5, v7, v5, 2
	v_add_u32_e32 v234, 0, v5
	v_add_u32_e32 v235, s2, v5
	v_cndmask_b32_e64 v5, v15, v14, s[44:45]
	v_add_lshl_u32 v5, v7, v5, 2
	v_add_u32_e32 v236, 0, v5
	v_add_u32_e32 v237, s2, v5
	v_cndmask_b32_e64 v5, v17, v13, s[44:45]
	v_add_lshl_u32 v5, v7, v5, 2
	v_readlane_b32 s25, v253, 25
	v_add_u32_e32 v238, 0, v5
	v_add_u32_e32 v239, s2, v5
	v_cndmask_b32_e64 v5, v16, v12, s[44:45]
	s_addc_u32 s55, s25, s5
	v_lshlrev_b32_e32 v94, 3, v1
	v_add_lshl_u32 v5, v7, v5, 2
	s_add_u32 s58, s86, 0x740000
	v_and_b32_e32 v2, 56, v94
	v_add_u32_e32 v240, 0, v5
	v_add_u32_e32 v241, s2, v5
	v_cndmask_b32_e64 v5, v10, v9, s[44:45]
	v_cndmask_b32_e64 v8, 0, v8, s[44:45]
	s_addc_u32 s59, s94, 0
	v_add_lshl_u32 v5, v7, v5, 2
	v_add_lshl_u32 v7, v7, v8, 2
	v_lshlrev_b32_e32 v8, 2, v2
	s_cmp_eq_u32 s83, 3
	v_add3_u32 v242, s2, v11, v8
	v_add_u32_e32 v244, s2, v5
	v_add_u32_e32 v247, s2, v7
	v_readlane_b32 s2, v251, 26
	s_cselect_b64 s[60:61], -1, 0
	s_cmp_lg_u32 s83, 3
	v_lshl_add_u32 v3, v41, 2, 0
	v_cmp_lt_i32_e32 vcc, s14, v1
	v_add_u32_e32 v243, 0, v5
	v_mov_b32_e32 v5, v0
	v_readlane_b32 s3, v251, 27
	s_cselect_b64 s[62:63], -1, 0
	v_ashrrev_i32_e32 v93, 31, v92
	v_add_u32_e32 v60, 0x480, v58
	v_add_u32_e32 v61, 0x900, v58
	v_add_u32_e32 v62, 0xd80, v58
	v_add_u32_e32 v63, 0x1200, v58
	v_add_u32_e32 v64, 0x1680, v58
	v_add_u32_e32 v65, 0x1b00, v58
	v_add_u32_e32 v245, v3, v6
	v_add_u32_e32 v246, 0, v7
	v_lshl_add_u64 v[90:91], s[2:3], 0, v[4:5]
	v_mov_b32_e32 v35, v0
	s_mov_b32 s4, -1
	s_mov_b32 s99, 0
	s_xor_b64 s[64:65], vcc, -1
	v_lshlrev_b32_e32 v44, 1, v2
	v_add_u32_e32 v248, 0x1f80, v58
	v_readlane_b32 s21, v253, 21
	v_readlane_b32 s26, v253, 26
	v_readlane_b32 s27, v253, 27
	s_branch .LBB0_591

; #define LAS __attribute__((address_space(3)))
; __device__ __forceinline__ void lru_pass(LAS unsigned char* L, int mode, const bf16_t* Z, const bf16_t* LWT, const float* conv_w, const float* conv_b, const float* b_a, const float* b_x, const float* lam,
;                          float* LSUM, const float* LCAR, bf16_t* Y) {
;     ...
;         { LAS bf16_t* XS = (LAS bf16_t*)(L + 129280);
;             for (int idx = tid; idx < 536; idx += 512) { const int rr = idx >> 3, sg = idx & 7, tt = seg * 64 - 2 + rr; bf16x8 v = (bf16x8){0, 0, 0, 0, 0, 0, 0, 0};
;                 if (tt >= 0 && tt < S_) v = *(const bf16x8*)(Z + ((size_t)b * S_ + tt) * 2560 + 1536 + n * 64 + sg * 8);
;                 *(LAS bf16x8*)(XS + rr * 72 + sg * 8) = v; }
.LBB0_596:
	v_ashrrev_i32_e32 v9, 3, v8
	v_add_u32_e32 v10, s5, v9
	s_movk_i32 s7, 0x4000
	v_cmp_gt_u32_e32 vcc, s7, v10
	v_mov_b32_e32 v2, 0
	v_mov_b32_e32 v3, 0
	v_mov_b32_e32 v4, 0
	v_mov_b32_e32 v5, 0
	s_and_saveexec_b64 s[26:27], vcc
	s_cbranch_execz .LBB0_595
	s_cmp_lg_u32 s99, 0
	s_cbranch_scc1 .Llru_xs_st
	v_or_b32_e32 v2, s22, v10
	v_mad_u64_u32 v[2:3], s[8:9], v2, s10, v[6:7]
	v_mov_b32_e32 v4, 0x1400
	v_mad_i32_i24 v3, s23, v4, v3
	global_load_dwordx4 v[2:5], v[2:3], off offset:3072
	s_branch .LBB0_595
.Llru_xs_st:
	v_lshlrev_b32_e32 v2, 4, v8
	v_add_u32_e32 v2, 0x24a00, v2
	s_waitcnt vmcnt(0)
	ds_read_b128 v[2:5], v2
	s_waitcnt lgkmcnt(0)
	s_branch .LBB0_595

; #define LAS __attribute__((address_space(3)))
; __device__ __forceinline__ int obid() { int b = __builtin_amdgcn_workgroup_id_x(); asm volatile("" : "+s"(b)); return b; }
; __device__ __forceinline__ float sigm(float x) { return __builtin_amdgcn_rcpf(1.f + __expf(-x)); }
; __device__ __forceinline__ void lru_pass(LAS unsigned char* L, int mode, const bf16_t* Z, const bf16_t* LWT, const float* conv_w, const float* conv_b, const float* b_a, const float* b_x, const float* lam,
;                          float* LSUM, const float* LCAR, bf16_t* Y) {
;     ...
;     for (int item = obid(); item < 4096; item += gridDim.x) {
;         const int b = item >> 11, seg = (item >> 3) & 255, n = item & 7;
;         { LAS bf16_t* XS = (LAS bf16_t*)(L + 129280);
;             for (int idx = tid; idx < 536; idx += 512) { const int rr = idx >> 3, sg = idx & 7, tt = seg * 64 - 2 + rr; bf16x8 v = (bf16x8){0, 0, 0, 0, 0, 0, 0, 0};
;                 if (tt >= 0 && tt < S_) v = *(const bf16x8*)(Z + ((size_t)b * S_ + tt) * 2560 + 1536 + n * 64 + sg * 8);
;                 *(LAS bf16x8*)(XS + rr * 72 + sg * 8) = v; }
;     ...
;             for (int td = 0; td < 4; ++td) { const int d = td * 16 + fr, ch = n * 64 + d; const float lm = lam[g * 512 + ch]; const float sp = lm > 0.f ? log1pf(expf(-lm)) : -lm + log1pf(expf(lm));
;                 const float ba_ = b_a[g * 512 + ch], bx_ = b_x[g * 512 + ch];
; #pragma unroll
;                 for (int r = 0; r < 4; ++r) { const int i = ti * 16 + 4 * fq + r; const float la = -8.f * sigm(aa[td][r] + ba_) * sp;
;                     const float a_ = __expf(la), x2 = 2.f * la; const float om = (x2 > -0.02f) ? -x2 * (1.f + x2 * (0.5f + x2 * (1.f / 6.f))) : 1.f - a_ * a_;
;                     AA[g * 4160 + i * 65 + d] = a_; UU[g * 4160 + i * 65 + d] = __builtin_amdgcn_sqrtf(om) * sigm(ax[td][r] + bx_) * xc[i * 65 + d]; } } }
;         __syncthreads();
.Llru_c3_e:
	v_add_f32_e32 v2, v2, v14
	v_mul_f32_e32 v2, 0xbfb8aa3b, v2
	v_exp_f32_e32 v2, v2
	v_add_f32_e32 v6, 1.0, v6
	v_rcp_f32_e32 v13, v6
	v_add_f32_e32 v6, v7, v11
	v_mul_f32_e32 v6, 0xbfb8aa3b, v6
	v_exp_f32_e32 v6, v6
	v_add_f32_e32 v2, 1.0, v2
	v_rcp_f32_e32 v2, v2
	v_add_f32_e32 v3, v3, v14
	v_add_f32_e32 v6, 1.0, v6
	v_rcp_f32_e32 v12, v6
	v_mul_f32_e32 v3, 0xbfb8aa3b, v3
	v_exp_f32_e32 v3, v3
	v_pk_mul_f32 v[6:7], v[12:13], s[4:5] op_sel_hi:[1,0]
	s_nop 0
	v_pk_mul_f32 v[6:7], v[10:11], v[6:7] op_sel_hi:[0,1]
	v_mul_f32_e32 v12, 0x3fb8aa3b, v7
	v_exp_f32_e32 v15, v12
	v_pk_add_f32 v[12:13], v[6:7], v[6:7]
	v_add_f32_e32 v3, 1.0, v3
	v_fma_f32 v7, v13, s2, 0.5
	v_fma_f32 v7, v13, v7, 1.0
	v_mul_f32_e64 v7, v7, -v13
	v_fma_f32 v16, -v15, v15, 1.0
	v_cmp_lt_f32_e64 s[44:45], s3, v13
	ds_write_b32 v68, v15 offset:62912
	v_cmp_lt_f32_e32 vcc, s3, v12
	v_cndmask_b32_e64 v7, v16, v7, s[44:45]
	v_sqrt_f32_e32 v7, v7
	v_rcp_f32_e32 v3, v3
	v_mul_f32_e32 v2, v2, v7
	ds_read_b32 v7, v69 offset:192
	s_waitcnt lgkmcnt(0)
	v_mul_f32_e32 v2, v7, v2
	ds_write_b32 v84, v2
	v_mul_f32_e32 v2, 0x3fb8aa3b, v6
	v_exp_f32_e32 v2, v2
	v_fma_f32 v6, v12, s2, 0.5
	v_fma_f32 v6, v12, v6, 1.0
	v_mul_f32_e64 v6, v6, -v12
	v_fma_f32 v7, -v2, v2, 1.0
	v_cndmask_b32_e32 v6, v7, v6, vcc
	ds_write_b32 v85, v2 offset:62980
	v_sqrt_f32_e32 v2, v6
	s_nop 0
	v_mul_f32_e32 v2, v3, v2
	ds_read_b32 v3, v69 offset:452
	s_waitcnt lgkmcnt(0)
	v_mul_f32_e32 v2, v3, v2
	ds_write_b32 v86, v2
	v_add_f32_e32 v2, v8, v11
	v_mul_f32_e32 v2, 0xbfb8aa3b, v2
	v_exp_f32_e32 v2, v2
	s_nop 0
	v_add_f32_e32 v2, 1.0, v2
	v_rcp_f32_e32 v3, v2
	v_add_f32_e32 v2, v4, v14
	v_mul_f32_e32 v2, 0xbfb8aa3b, v2
	v_exp_f32_e32 v2, v2
	s_nop 0
	v_add_f32_e32 v2, 1.0, v2
	v_rcp_f32_e32 v4, v2
	v_add_f32_e32 v2, v9, v11
	v_mul_f32_e32 v2, 0xbfb8aa3b, v2
	v_exp_f32_e32 v2, v2
	s_nop 0
	v_add_f32_e32 v2, 1.0, v2
	v_rcp_f32_e32 v2, v2
	s_nop 0
	v_pk_mul_f32 v[2:3], v[2:3], s[4:5] op_sel_hi:[1,0]
	s_nop 0
	v_pk_mul_f32 v[2:3], v[10:11], v[2:3] op_sel_hi:[0,1]
	v_mul_f32_e32 v6, 0x3fb8aa3b, v3
	v_exp_f32_e32 v8, v6
	v_pk_add_f32 v[6:7], v[2:3], v[2:3]
	v_mul_f32_e32 v2, 0x3fb8aa3b, v2
	v_fma_f32 v3, v7, s2, 0.5
	v_fma_f32 v3, v7, v3, 1.0
	v_mul_f32_e64 v3, v3, -v7
	v_fma_f32 v9, -v8, v8, 1.0
	v_cmp_lt_f32_e64 s[44:45], s3, v7
	ds_write_b32 v85, v8 offset:63240
	v_exp_f32_e32 v2, v2
	v_cndmask_b32_e64 v3, v9, v3, s[44:45]
	v_sqrt_f32_e32 v3, v3
	v_cmp_lt_f32_e32 vcc, s3, v6
	v_mul_f32_e32 v3, v4, v3
	ds_read_b32 v4, v69 offset:712
	s_waitcnt lgkmcnt(0)
	v_mul_f32_e32 v3, v4, v3
	ds_write_b32 v87, v3
	v_fma_f32 v3, v6, s2, 0.5
	v_fma_f32 v3, v6, v3, 1.0
	v_mul_f32_e64 v3, v3, -v6
	v_fma_f32 v4, -v2, v2, 1.0
	v_cndmask_b32_e32 v3, v4, v3, vcc
	ds_write_b32 v85, v2 offset:63500
	v_sqrt_f32_e32 v2, v3
	v_add_f32_e32 v3, v5, v14
	v_mul_f32_e32 v3, 0xbfb8aa3b, v3
	v_exp_f32_e32 v3, v3
	s_nop 0
	v_add_f32_e32 v3, 1.0, v3
	v_rcp_f32_e32 v3, v3
	s_nop 0
	v_mul_f32_e32 v2, v3, v2
	ds_read_b32 v3, v69 offset:972
	s_waitcnt lgkmcnt(0)
	v_mul_f32_e32 v2, v3, v2
	ds_write_b32 v88, v2
	s_waitcnt lgkmcnt(0)
	s_barrier
	s_mov_b32 s99, 0
	s_add_i32 s4, s38, s96
	s_cmpk_gt_i32 s4, 0xfff
	s_cbranch_scc1 .Llru_xs_skip
	s_mov_b32 s99, 1
	s_ashr_i32 s8, s4, 11
	s_bfe_u32 s5, s4, 0x80003
	s_lshl_b32 s5, s5, 6
	s_add_i32 s5, s5, -2
	s_ashr_i32 s9, s8, 31
	s_lshl_b64 s[8:9], s[8:9], 14
	s_lshl_b32 s28, s39, 7
	s_add_i32 s28, s28, 0xc00
	v_lshl_add_u64 v[6:7], v[90:91], 0, s[28:29]
	v_lshrrev_b32_e32 v9, 6, v196
	v_mov_b32_e32 v4, 0x1400
	v_readfirstlane_b32 s4, v9
	s_movk_i32 s7, 0x4000
	s_nop 0
	s_lshl_b32 s4, s4, 10
	v_ashrrev_i32_e32 v9, 3, v196
	v_add_u32_e32 v10, s5, v9
	v_cmp_gt_u32_e32 vcc, s7, v10
	s_and_saveexec_b64 s[20:21], vcc
	s_cbranch_execz .Llru_xs_p1
	v_or_b32_e32 v2, s8, v10
	v_mad_u64_u32 v[2:3], s[22:23], v2, s10, v[6:7]
	v_mad_i32_i24 v3, s9, v4, v3
	s_add_i32 m0, s4, 0x24a00
	s_nop 0
	global_load_lds_dwordx4 v[2:3], off
.Llru_xs_p1:
	s_or_b64 exec, exec, s[20:21]
	v_add_u32_e32 v10, 64, v10
	v_cmp_gt_u32_e32 vcc, s7, v10
	v_cmp_gt_u32_e64 s[22:23], 24, v196
	s_nop 1
	s_and_b64 vcc, vcc, s[22:23]
	s_and_saveexec_b64 s[20:21], vcc
	s_cbranch_execz .Llru_xs_p2
	v_or_b32_e32 v2, s8, v10
	v_mad_u64_u32 v[2:3], s[22:23], v2, s10, v[6:7]
	v_mad_i32_i24 v3, s9, v4, v3
	s_mov_b32 m0, 0x26a00
	s_nop 0
	global_load_lds_dwordx4 v[2:3], off

; __device__ __forceinline__ void lru_pass(LAS unsigned char* L, int mode, const bf16_t* Z, const bf16_t* LWT, const float* conv_w, const float* conv_b, const float* b_a, const float* b_x, const float* lam,
;                          float* LSUM, const float* LCAR, bf16_t* Y) {
;     ...
;         if (mode == 1) {
;             { const int i = tid >> 3, sg = tid & 7; const size_t row = (size_t)b * S_ + seg * 64 + i;
;                 const bf16x8 gv = *(const bf16x8*)(Z + row * 2560 + 2048 + n * 64 + sg * 8); float y[8];
.Llru_xs_skip:
	s_and_b64 vcc, exec, s[60:61]
	s_cbranch_vccz .Llru_gv_skip
	s_ashr_i32 s9, s66, 31
	s_mov_b32 s8, s66
	s_lshl_b64 s[4:5], s[8:9], 14
	s_lshl_b32 s6, s68, 6
	s_or_b32 s4, s4, s6
	v_readlane_b32 s8, v251, 26
	v_readlane_b32 s9, v251, 27
	v_lshl_add_u64 v[6:7], s[4:5], 0, v[92:93]
	s_nop 1
	v_mov_b64_e32 v[2:3], s[8:9]
	v_mad_u64_u32 v[2:3], s[4:5], v6, s10, v[2:3]
	v_mad_i32_i24 v3, v7, s10, v3
	v_mov_b32_e32 v8, v46
	v_mov_b32_e32 v9, v0
	v_lshlrev_b64 v[8:9], 1, v[8:9]
	v_lshl_add_u64 v[2:3], v[2:3], 0, v[8:9]
	v_mov_b32_e32 v8, v44
	v_mov_b32_e32 v9, v0
	v_lshl_add_u64 v[2:3], v[2:3], 0, v[8:9]
	v_add_co_u32_e32 v2, vcc, 0x1000, v2
	s_nop 1
	v_addc_co_u32_e32 v3, vcc, 0, v3, vcc
	v_lshrrev_b32_e32 v4, 6, v196
	s_nop 0
	v_readfirstlane_b32 s4, v4
	s_nop 1
	s_lshl_b32 s4, s4, 10
	s_add_i32 m0, s4, 0x22a00
	s_nop 0
	global_load_lds_dwordx4 v[2:3], off
